# router reduction: lane^1 / lane^2 exchanges via DPP quad_perm instead of ds_bpermute (on top of v36)
# speedup vs baseline: 1.0154x; 1.0003x over previous
; __global__ void __launch_bounds__(NTHR) fwd_megakernel(Params p) {
;     ...
;       for (int e = 0; e < 16; ++e) {
;         float a4[4] = {0.f, 0.f, 0.f, 0.f};
; #pragma unroll
;         for (int i = 0; i < 4; ++i) {
;           const float4 w = *(const float4*)(wr + e * 1028 + i * 256 + lane * 4);
; #pragma unroll
;           for (int rr = 0; rr < 4; ++rr)
;             a4[rr] += yv[rr][i * 4] * w.x + yv[rr][i * 4 + 1] * w.y + yv[rr][i * 4 + 2] * w.z + yv[rr][i * 4 + 3] * w.w;
;         }
.LBB0_1023:
.Lrt_loop:
	v_add_u32_e32 v1, s14, v102
	ds_read_b128 v[20:23], v1
	ds_read_b128 v[32:35], v1 offset:1024
	ds_read_b128 v[130:133], v1 offset:2048
	ds_read_b128 v[134:137], v1 offset:3072
	s_waitcnt lgkmcnt(3)
	v_mul_f32_e32 v1, v21, v118
	v_mul_f32_e32 v5, v21, v121
	v_mul_f32_e32 v100, v21, v61
	v_mul_f32_e32 v101, v21, v65
	s_waitcnt lgkmcnt(2)
	v_mul_f32_e32 v126, v33, v67
	v_mul_f32_e32 v127, v33, v95
	v_mul_f32_e32 v129, v33, v125
	v_mul_f32_e32 v138, v33, v57
	s_waitcnt lgkmcnt(0)
	v_mov_b32_e32 v7, v134
	v_mov_b32_e32 v134, v131
	v_fmac_f32_e32 v1, v20, v117
	v_fmac_f32_e32 v5, v20, v91
	v_fmac_f32_e32 v100, v20, v60
	v_fmac_f32_e32 v101, v20, v64
	v_mov_b32_e32 v6, v130
	v_fmac_f32_e32 v126, v32, v66
	v_fmac_f32_e32 v127, v32, v94
	v_fmac_f32_e32 v129, v32, v124
	v_fmac_f32_e32 v138, v32, v56
	v_pk_mul_f32 v[20:21], v[134:135], v[24:25]
	v_pk_mul_f32 v[32:33], v[134:135], v[28:29]
	v_pk_mul_f32 v[58:59], v[134:135], v[36:37]
	v_pk_mul_f32 v[96:97], v[134:135], v[44:45]
	v_fmac_f32_e32 v1, v22, v119
	v_fmac_f32_e32 v5, v22, v122
	v_fmac_f32_e32 v100, v22, v62
	v_fmac_f32_e32 v101, v22, v10
	v_mov_b32_e32 v12, v132
	v_mov_b32_e32 v13, v136
	v_fmac_f32_e32 v126, v34, v92
	v_fmac_f32_e32 v127, v34, v98
	v_fmac_f32_e32 v129, v34, v54
	v_fmac_f32_e32 v138, v34, v42
	v_pk_fma_f32 v[20:21], v[6:7], v[8:9], v[20:21]
	v_pk_fma_f32 v[32:33], v[6:7], v[16:17], v[32:33]
	v_pk_fma_f32 v[58:59], v[6:7], v[30:31], v[58:59]
	v_pk_fma_f32 v[6:7], v[6:7], v[40:41], v[96:97]
	v_fmac_f32_e32 v1, v23, v120
	v_fmac_f32_e32 v5, v23, v123
	v_fmac_f32_e32 v100, v23, v63
	v_fmac_f32_e32 v101, v23, v11
	v_mov_b32_e32 v136, v133
	v_fmac_f32_e32 v126, v35, v93
	v_fmac_f32_e32 v127, v35, v99
	v_fmac_f32_e32 v129, v35, v55
	v_fmac_f32_e32 v138, v35, v43
	v_pk_fma_f32 v[20:21], v[12:13], v[26:27], v[20:21]
	v_pk_fma_f32 v[22:23], v[12:13], v[18:19], v[32:33]
	v_pk_fma_f32 v[32:33], v[12:13], v[38:39], v[58:59]
	v_pk_fma_f32 v[6:7], v[12:13], v[46:47], v[6:7]
	v_add_f32_e32 v1, 0, v1
	v_add_f32_e32 v5, 0, v5
	v_add_f32_e32 v34, 0, v100
	v_add_f32_e32 v35, 0, v101
	v_pk_fma_f32 v[12:13], v[136:137], v[48:49], v[20:21]
	v_pk_fma_f32 v[20:21], v[136:137], v[50:51], v[22:23]
	v_pk_fma_f32 v[22:23], v[136:137], v[52:53], v[32:33]
	v_pk_fma_f32 v[6:7], v[136:137], v[14:15], v[6:7]
	v_add_f32_e32 v1, v1, v126
	v_add_f32_e32 v5, v5, v127
	v_add_f32_e32 v32, v34, v129
	v_add_f32_e32 v33, v35, v138
	v_add_f32_e32 v1, v1, v12
	v_add_f32_e32 v5, v5, v20
	v_add_f32_e32 v12, v32, v22
	v_add_f32_e32 v6, v33, v6
	v_add_f32_e32 v1, v1, v13
	v_add_f32_e32 v5, v5, v21
	v_add_f32_e32 v12, v12, v23
	v_add_f32_e32 v6, v6, v7
	v_mov_b32_e32 v236, v1
	v_mov_b32_e32 v237, v5
	v_mov_b32_e32 v238, v12
	v_mov_b32_e32 v239, v6
	s_addk_i32 s14, 0x1010
	v_add_u32_e32 v1, s14, v102
	ds_read_b128 v[20:23], v1
	ds_read_b128 v[32:35], v1 offset:1024
	ds_read_b128 v[130:133], v1 offset:2048
	ds_read_b128 v[134:137], v1 offset:3072
	s_waitcnt lgkmcnt(3)
	v_mul_f32_e32 v1, v21, v118
	v_mul_f32_e32 v5, v21, v121
	v_mul_f32_e32 v100, v21, v61
	v_mul_f32_e32 v101, v21, v65
	s_waitcnt lgkmcnt(2)
	v_mul_f32_e32 v126, v33, v67
	v_mul_f32_e32 v127, v33, v95
	v_mul_f32_e32 v129, v33, v125
	v_mul_f32_e32 v138, v33, v57
	s_waitcnt lgkmcnt(0)
	v_mov_b32_e32 v7, v134
	v_mov_b32_e32 v134, v131
	v_fmac_f32_e32 v1, v20, v117
	v_fmac_f32_e32 v5, v20, v91
	v_fmac_f32_e32 v100, v20, v60
	v_fmac_f32_e32 v101, v20, v64
	v_mov_b32_e32 v6, v130
	v_fmac_f32_e32 v126, v32, v66
	v_fmac_f32_e32 v127, v32, v94
	v_fmac_f32_e32 v129, v32, v124
	v_fmac_f32_e32 v138, v32, v56
	v_pk_mul_f32 v[20:21], v[134:135], v[24:25]
	v_pk_mul_f32 v[32:33], v[134:135], v[28:29]
	v_pk_mul_f32 v[58:59], v[134:135], v[36:37]
	v_pk_mul_f32 v[96:97], v[134:135], v[44:45]
	v_fmac_f32_e32 v1, v22, v119
	v_fmac_f32_e32 v5, v22, v122
	v_fmac_f32_e32 v100, v22, v62
	v_fmac_f32_e32 v101, v22, v10
	v_mov_b32_e32 v12, v132
	v_mov_b32_e32 v13, v136
	v_fmac_f32_e32 v126, v34, v92
	v_fmac_f32_e32 v127, v34, v98
	v_fmac_f32_e32 v129, v34, v54
	v_fmac_f32_e32 v138, v34, v42
	v_pk_fma_f32 v[20:21], v[6:7], v[8:9], v[20:21]
	v_pk_fma_f32 v[32:33], v[6:7], v[16:17], v[32:33]
	v_pk_fma_f32 v[58:59], v[6:7], v[30:31], v[58:59]
	v_pk_fma_f32 v[6:7], v[6:7], v[40:41], v[96:97]
	v_fmac_f32_e32 v1, v23, v120
	v_fmac_f32_e32 v5, v23, v123
	v_fmac_f32_e32 v100, v23, v63
	v_fmac_f32_e32 v101, v23, v11
	v_mov_b32_e32 v136, v133
	v_fmac_f32_e32 v126, v35, v93
	v_fmac_f32_e32 v127, v35, v99
	v_fmac_f32_e32 v129, v35, v55
	v_fmac_f32_e32 v138, v35, v43
	v_pk_fma_f32 v[20:21], v[12:13], v[26:27], v[20:21]
	v_pk_fma_f32 v[22:23], v[12:13], v[18:19], v[32:33]
	v_pk_fma_f32 v[32:33], v[12:13], v[38:39], v[58:59]
	v_pk_fma_f32 v[6:7], v[12:13], v[46:47], v[6:7]
	v_add_f32_e32 v1, 0, v1
	v_add_f32_e32 v5, 0, v5
	v_add_f32_e32 v34, 0, v100
	v_add_f32_e32 v35, 0, v101
	v_pk_fma_f32 v[12:13], v[136:137], v[48:49], v[20:21]
	v_pk_fma_f32 v[20:21], v[136:137], v[50:51], v[22:23]
	v_pk_fma_f32 v[22:23], v[136:137], v[52:53], v[32:33]
	v_pk_fma_f32 v[6:7], v[136:137], v[14:15], v[6:7]
	v_add_f32_e32 v1, v1, v126
	v_add_f32_e32 v5, v5, v127
	v_add_f32_e32 v32, v34, v129
	v_add_f32_e32 v33, v35, v138
	v_add_f32_e32 v1, v1, v12
	v_add_f32_e32 v5, v5, v20
	v_add_f32_e32 v12, v32, v22
	v_add_f32_e32 v6, v33, v6
	v_add_f32_e32 v1, v1, v13
	v_add_f32_e32 v5, v5, v21
	v_add_f32_e32 v12, v12, v23
	v_add_f32_e32 v6, v6, v7
	v_mov_b32_e32 v241, v1
	v_mov_b32_e32 v242, v5
	v_mov_b32_e32 v243, v12
	v_mov_b32_e32 v244, v6
	s_addk_i32 s14, 0x1010
	v_add_u32_e32 v1, s14, v102
	ds_read_b128 v[20:23], v1
	ds_read_b128 v[32:35], v1 offset:1024
	ds_read_b128 v[130:133], v1 offset:2048
	ds_read_b128 v[134:137], v1 offset:3072
	s_waitcnt lgkmcnt(3)
; __global__ void __launch_bounds__(NTHR) fwd_megakernel(Params p) {
;     ...
;       for (int e = 0; e < 16; ++e) {
;         float a4[4] = {0.f, 0.f, 0.f, 0.f};
; #pragma unroll
;         for (int i = 0; i < 4; ++i) {
;           const float4 w = *(const float4*)(wr + e * 1028 + i * 256 + lane * 4);
; #pragma unroll
;           for (int rr = 0; rr < 4; ++rr)
;             a4[rr] += yv[rr][i * 4] * w.x + yv[rr][i * 4 + 1] * w.y + yv[rr][i * 4 + 2] * w.z + yv[rr][i * 4 + 3] * w.w;
;         }
;         float r2[2];
;         { const bool hi = lane & 1;
;           const float s0 = hi ? a4[0] : a4[1], k0 = hi ? a4[1] : a4[0];
;           const float s1 = hi ? a4[2] : a4[3], k1 = hi ? a4[3] : a4[2];
	v_mul_f32_e32 v1, v21, v118
	v_mul_f32_e32 v5, v21, v121
	v_mul_f32_e32 v100, v21, v61
	v_mul_f32_e32 v101, v21, v65
	s_waitcnt lgkmcnt(2)
	v_mul_f32_e32 v126, v33, v67
	v_mul_f32_e32 v127, v33, v95
	v_mul_f32_e32 v129, v33, v125
	v_mul_f32_e32 v138, v33, v57
	s_waitcnt lgkmcnt(0)
	v_mov_b32_e32 v7, v134
	v_mov_b32_e32 v134, v131
	v_fmac_f32_e32 v1, v20, v117
	v_fmac_f32_e32 v5, v20, v91
	v_fmac_f32_e32 v100, v20, v60
	v_fmac_f32_e32 v101, v20, v64
	v_mov_b32_e32 v6, v130
	v_fmac_f32_e32 v126, v32, v66
	v_fmac_f32_e32 v127, v32, v94
	v_fmac_f32_e32 v129, v32, v124
	v_fmac_f32_e32 v138, v32, v56
	v_pk_mul_f32 v[20:21], v[134:135], v[24:25]
	v_pk_mul_f32 v[32:33], v[134:135], v[28:29]
	v_pk_mul_f32 v[58:59], v[134:135], v[36:37]
	v_pk_mul_f32 v[96:97], v[134:135], v[44:45]
	v_fmac_f32_e32 v1, v22, v119
	v_fmac_f32_e32 v5, v22, v122
	v_fmac_f32_e32 v100, v22, v62
	v_fmac_f32_e32 v101, v22, v10
	v_mov_b32_e32 v12, v132
	v_mov_b32_e32 v13, v136
	v_fmac_f32_e32 v126, v34, v92
	v_fmac_f32_e32 v127, v34, v98
	v_fmac_f32_e32 v129, v34, v54
	v_fmac_f32_e32 v138, v34, v42
	v_pk_fma_f32 v[20:21], v[6:7], v[8:9], v[20:21]
	v_pk_fma_f32 v[32:33], v[6:7], v[16:17], v[32:33]
	v_pk_fma_f32 v[58:59], v[6:7], v[30:31], v[58:59]
	v_pk_fma_f32 v[6:7], v[6:7], v[40:41], v[96:97]
	v_fmac_f32_e32 v1, v23, v120
	v_fmac_f32_e32 v5, v23, v123
	v_fmac_f32_e32 v100, v23, v63
	v_fmac_f32_e32 v101, v23, v11
	v_mov_b32_e32 v136, v133
	v_fmac_f32_e32 v126, v35, v93
	v_fmac_f32_e32 v127, v35, v99
	v_fmac_f32_e32 v129, v35, v55
	v_fmac_f32_e32 v138, v35, v43
	v_pk_fma_f32 v[20:21], v[12:13], v[26:27], v[20:21]
	v_pk_fma_f32 v[22:23], v[12:13], v[18:19], v[32:33]
	v_pk_fma_f32 v[32:33], v[12:13], v[38:39], v[58:59]
	v_pk_fma_f32 v[6:7], v[12:13], v[46:47], v[6:7]
	v_add_f32_e32 v1, 0, v1
	v_add_f32_e32 v5, 0, v5
	v_add_f32_e32 v34, 0, v100
	v_add_f32_e32 v35, 0, v101
	v_pk_fma_f32 v[12:13], v[136:137], v[48:49], v[20:21]
	v_pk_fma_f32 v[20:21], v[136:137], v[50:51], v[22:23]
	v_pk_fma_f32 v[22:23], v[136:137], v[52:53], v[32:33]
	v_pk_fma_f32 v[6:7], v[136:137], v[14:15], v[6:7]
	v_add_f32_e32 v1, v1, v126
	v_add_f32_e32 v5, v5, v127
	v_add_f32_e32 v32, v34, v129
	v_add_f32_e32 v33, v35, v138
	v_add_f32_e32 v1, v1, v12
	v_add_f32_e32 v5, v5, v20
	v_add_f32_e32 v12, v32, v22
	v_add_f32_e32 v6, v33, v6
	v_add_f32_e32 v1, v1, v13
	v_add_f32_e32 v5, v5, v21
	v_add_f32_e32 v12, v12, v23
	v_add_f32_e32 v6, v6, v7
	v_mov_b32_e32 v246, v1
	v_mov_b32_e32 v247, v5
	v_mov_b32_e32 v248, v12
	v_mov_b32_e32 v249, v6
	s_addk_i32 s14, 0x1010
	v_add_u32_e32 v1, s14, v102
	ds_read_b128 v[20:23], v1
	ds_read_b128 v[32:35], v1 offset:1024
	ds_read_b128 v[130:133], v1 offset:2048
	ds_read_b128 v[134:137], v1 offset:3072
	s_waitcnt lgkmcnt(3)
	v_mul_f32_e32 v1, v21, v118
	v_mul_f32_e32 v5, v21, v121
	v_mul_f32_e32 v100, v21, v61
	v_mul_f32_e32 v101, v21, v65
	s_waitcnt lgkmcnt(2)
	v_mul_f32_e32 v126, v33, v67
	v_mul_f32_e32 v127, v33, v95
	v_mul_f32_e32 v129, v33, v125
	v_mul_f32_e32 v138, v33, v57
	s_waitcnt lgkmcnt(0)
	v_mov_b32_e32 v7, v134
	v_mov_b32_e32 v134, v131
	v_fmac_f32_e32 v1, v20, v117
	v_fmac_f32_e32 v5, v20, v91
	v_fmac_f32_e32 v100, v20, v60
	v_fmac_f32_e32 v101, v20, v64
	v_mov_b32_e32 v6, v130
	v_fmac_f32_e32 v126, v32, v66
	v_fmac_f32_e32 v127, v32, v94
	v_fmac_f32_e32 v129, v32, v124
	v_fmac_f32_e32 v138, v32, v56
	v_pk_mul_f32 v[20:21], v[134:135], v[24:25]
	v_pk_mul_f32 v[32:33], v[134:135], v[28:29]
	v_pk_mul_f32 v[58:59], v[134:135], v[36:37]
	v_pk_mul_f32 v[96:97], v[134:135], v[44:45]
	v_fmac_f32_e32 v1, v22, v119
	v_fmac_f32_e32 v5, v22, v122
	v_fmac_f32_e32 v100, v22, v62
	v_fmac_f32_e32 v101, v22, v10
	v_mov_b32_e32 v12, v132
	v_mov_b32_e32 v13, v136
	v_fmac_f32_e32 v126, v34, v92
	v_fmac_f32_e32 v127, v34, v98
	v_fmac_f32_e32 v129, v34, v54
	v_fmac_f32_e32 v138, v34, v42
	v_pk_fma_f32 v[20:21], v[6:7], v[8:9], v[20:21]
	v_pk_fma_f32 v[32:33], v[6:7], v[16:17], v[32:33]
	v_pk_fma_f32 v[58:59], v[6:7], v[30:31], v[58:59]
	v_pk_fma_f32 v[6:7], v[6:7], v[40:41], v[96:97]
	v_fmac_f32_e32 v1, v23, v120
	v_fmac_f32_e32 v5, v23, v123
	v_fmac_f32_e32 v100, v23, v63
	v_fmac_f32_e32 v101, v23, v11
	v_mov_b32_e32 v136, v133
	v_fmac_f32_e32 v126, v35, v93
	v_fmac_f32_e32 v127, v35, v99
	v_fmac_f32_e32 v129, v35, v55
	v_fmac_f32_e32 v138, v35, v43
	v_pk_fma_f32 v[20:21], v[12:13], v[26:27], v[20:21]
	v_pk_fma_f32 v[22:23], v[12:13], v[18:19], v[32:33]
	v_pk_fma_f32 v[32:33], v[12:13], v[38:39], v[58:59]
	v_pk_fma_f32 v[6:7], v[12:13], v[46:47], v[6:7]
	v_add_f32_e32 v1, 0, v1
	v_add_f32_e32 v5, 0, v5
	v_add_f32_e32 v34, 0, v100
	v_add_f32_e32 v35, 0, v101
	v_pk_fma_f32 v[12:13], v[136:137], v[48:49], v[20:21]
	v_pk_fma_f32 v[20:21], v[136:137], v[50:51], v[22:23]
	v_pk_fma_f32 v[22:23], v[136:137], v[52:53], v[32:33]
	v_pk_fma_f32 v[6:7], v[136:137], v[14:15], v[6:7]
	v_add_f32_e32 v1, v1, v126
	v_add_f32_e32 v5, v5, v127
	v_add_f32_e32 v32, v34, v129
	v_add_f32_e32 v33, v35, v138
	v_add_f32_e32 v1, v1, v12
	v_add_f32_e32 v5, v5, v20
	v_add_f32_e32 v12, v32, v22
	v_add_f32_e32 v6, v33, v6
	v_add_f32_e32 v1, v1, v13
	v_add_f32_e32 v5, v5, v21
	v_add_f32_e32 v12, v12, v23
	v_add_f32_e32 v6, v6, v7
	v_mov_b32_e32 v251, v1
	v_mov_b32_e32 v252, v5
	v_mov_b32_e32 v253, v12
	v_mov_b32_e32 v254, v6
	s_addk_i32 s14, 0x1010
	v_cndmask_b32_e64 v240, v236, v237, s[10:11]
	v_cndmask_b32_e64 v236, v237, v236, s[10:11]
	v_cndmask_b32_e64 v237, v238, v239, s[10:11]
	v_cndmask_b32_e64 v239, v239, v238, s[10:11]
	v_cndmask_b32_e64 v245, v241, v242, s[10:11]
	v_cndmask_b32_e64 v241, v242, v241, s[10:11]
	v_cndmask_b32_e64 v242, v243, v244, s[10:11]
	v_cndmask_b32_e64 v244, v244, v243, s[10:11]
; __global__ void __launch_bounds__(NTHR) fwd_megakernel(Params p) {
;     ...
;         float r2[2];
;         { const bool hi = lane & 1;
;           const float s0 = hi ? a4[0] : a4[1], k0 = hi ? a4[1] : a4[0];
;           const float s1 = hi ? a4[2] : a4[3], k1 = hi ? a4[3] : a4[2];
;           r2[0] = k0 + __shfl_xor(s0, 1); r2[1] = k1 + __shfl_xor(s1, 1); }
;         float r1;
;         { const bool hi = lane & 2;
;           const float s0 = hi ? r2[0] : r2[1], k0 = hi ? r2[1] : r2[0];
;           r1 = k0 + __shfl_xor(s0, 2); }
;         r1 += __shfl_xor(r1, 4); r1 += __shfl_xor(r1, 8); r1 += __shfl_xor(r1, 16); r1 += __shfl_xor(r1, 32);
; #pragma unroll
;         for (int rr = 0; rr < 4; ++rr) {
;           const float val = __shfl(r1, rr);
;           if (lane == e) mine[rr] = val;
;         }
;       }
; #pragma unroll
;       for (int rr = 0; rr < 4; ++rr) {
;         float lgv = (lane < 16) ? mine[rr] : -INFINITY;
;         float mxv = lgv;
; #pragma unroll
;         for (int o = 8; o > 0; o >>= 1) mxv = fmaxf(mxv, __shfl_xor(mxv, o));
;         mxv = __shfl(mxv, 0);
;         const float ex = (lane < 16) ? expf(lgv - mxv) : 0.f;
;         float den = ex;
; #pragma unroll
;         for (int o = 8; o > 0; o >>= 1) den += __shfl_xor(den, o);
;         den = __shfl(den, 0);
;         const int t = (row0 + rr) & 2047;
;         if (lane < 16) aff[((size_t)(b * 16 + lane)) * 2048 + t] = ex / den;
	v_cndmask_b32_e64 v250, v246, v247, s[10:11]
	v_cndmask_b32_e64 v246, v247, v246, s[10:11]
	v_cndmask_b32_e64 v247, v248, v249, s[10:11]
	v_cndmask_b32_e64 v249, v249, v248, s[10:11]
	v_cndmask_b32_e64 v255, v251, v252, s[10:11]
	v_cndmask_b32_e64 v251, v252, v251, s[10:11]
	v_cndmask_b32_e64 v252, v253, v254, s[10:11]
	v_cndmask_b32_e64 v254, v254, v253, s[10:11]
	s_nop 1
	v_add_f32_dpp v236, v240, v236 quad_perm:[1,0,3,2] row_mask:0xf bank_mask:0xf
	v_add_f32_dpp v237, v237, v239 quad_perm:[1,0,3,2] row_mask:0xf bank_mask:0xf
	v_add_f32_dpp v241, v245, v241 quad_perm:[1,0,3,2] row_mask:0xf bank_mask:0xf
	v_add_f32_dpp v242, v242, v244 quad_perm:[1,0,3,2] row_mask:0xf bank_mask:0xf
	v_add_f32_dpp v246, v250, v246 quad_perm:[1,0,3,2] row_mask:0xf bank_mask:0xf
	v_add_f32_dpp v247, v247, v249 quad_perm:[1,0,3,2] row_mask:0xf bank_mask:0xf
	v_add_f32_dpp v251, v255, v251 quad_perm:[1,0,3,2] row_mask:0xf bank_mask:0xf
	v_add_f32_dpp v252, v252, v254 quad_perm:[1,0,3,2] row_mask:0xf bank_mask:0xf
	v_cndmask_b32_e64 v239, v236, v237, s[12:13]
	v_cndmask_b32_e64 v236, v237, v236, s[12:13]
	v_cndmask_b32_e64 v244, v241, v242, s[12:13]
	v_cndmask_b32_e64 v241, v242, v241, s[12:13]
	v_cndmask_b32_e64 v249, v246, v247, s[12:13]
	v_cndmask_b32_e64 v246, v247, v246, s[12:13]
	v_cndmask_b32_e64 v254, v251, v252, s[12:13]
	v_cndmask_b32_e64 v251, v252, v251, s[12:13]
	s_nop 1
	v_add_f32_dpp v236, v239, v236 quad_perm:[2,3,0,1] row_mask:0xf bank_mask:0xf
	v_add_f32_dpp v241, v244, v241 quad_perm:[2,3,0,1] row_mask:0xf bank_mask:0xf
	v_add_f32_dpp v246, v249, v246 quad_perm:[2,3,0,1] row_mask:0xf bank_mask:0xf
	v_add_f32_dpp v251, v254, v251 quad_perm:[2,3,0,1] row_mask:0xf bank_mask:0xf
	s_nop 1
	ds_bpermute_b32 v237, v106, v236
	ds_bpermute_b32 v242, v106, v241
	ds_bpermute_b32 v247, v106, v246
	ds_bpermute_b32 v252, v106, v251
	s_waitcnt lgkmcnt(0)
	v_add_f32_e32 v236, v236, v237
	v_add_f32_e32 v241, v241, v242
	v_add_f32_e32 v246, v246, v247
	v_add_f32_e32 v251, v251, v252
	ds_bpermute_b32 v237, v105, v236
	ds_bpermute_b32 v242, v105, v241
	ds_bpermute_b32 v247, v105, v246
	ds_bpermute_b32 v252, v105, v251
	s_waitcnt lgkmcnt(0)
	v_add_f32_e32 v236, v236, v237
	v_add_f32_e32 v241, v241, v242
	v_add_f32_e32 v246, v246, v247
	v_add_f32_e32 v251, v251, v252
	ds_bpermute_b32 v237, v104, v236
	ds_bpermute_b32 v242, v104, v241
	ds_bpermute_b32 v247, v104, v246
	ds_bpermute_b32 v252, v104, v251
	s_waitcnt lgkmcnt(0)
	v_add_f32_e32 v236, v236, v237
	v_add_f32_e32 v241, v241, v242
	v_add_f32_e32 v246, v246, v247
	v_add_f32_e32 v251, v251, v252
	ds_bpermute_b32 v237, v103, v236
	ds_bpermute_b32 v242, v103, v241
	ds_bpermute_b32 v247, v103, v246
	ds_bpermute_b32 v252, v103, v251
	s_waitcnt lgkmcnt(0)
	v_add_f32_e32 v236, v236, v237
	v_add_f32_e32 v241, v241, v242
	v_add_f32_e32 v246, v246, v247
	v_add_f32_e32 v251, v251, v252
	ds_bpermute_b32 v237, v109, v236
	ds_bpermute_b32 v239, v110, v236
	ds_bpermute_b32 v240, v111, v236
	ds_bpermute_b32 v238, v112, v236
	ds_bpermute_b32 v242, v109, v241
	ds_bpermute_b32 v244, v110, v241
	ds_bpermute_b32 v245, v111, v241
	ds_bpermute_b32 v243, v112, v241
	ds_bpermute_b32 v247, v109, v246
	ds_bpermute_b32 v249, v110, v246
	ds_bpermute_b32 v250, v111, v246
	ds_bpermute_b32 v248, v112, v246
	ds_bpermute_b32 v252, v109, v251
	ds_bpermute_b32 v254, v110, v251
	ds_bpermute_b32 v255, v111, v251
	ds_bpermute_b32 v253, v112, v251
	s_waitcnt lgkmcnt(0)
	s_add_i32 s99, s14, 0xffffbfc0
	v_cmp_eq_u32_e32 vcc, s99, v114
	s_nop 1
	v_cndmask_b32_e32 v0, v0, v237, vcc
	v_cndmask_b32_e32 v4, v4, v239, vcc
	v_cndmask_b32_e32 v3, v3, v240, vcc
	v_cndmask_b32_e32 v2, v2, v238, vcc
	s_add_i32 s99, s14, 0xffffcfd0
	v_cmp_eq_u32_e32 vcc, s99, v114
	s_nop 1
	v_cndmask_b32_e32 v0, v0, v242, vcc
	v_cndmask_b32_e32 v4, v4, v244, vcc
	v_cndmask_b32_e32 v3, v3, v245, vcc
	v_cndmask_b32_e32 v2, v2, v243, vcc
	s_add_i32 s99, s14, 0xffffdfe0
	v_cmp_eq_u32_e32 vcc, s99, v114
	s_nop 1
	v_cndmask_b32_e32 v0, v0, v247, vcc
	v_cndmask_b32_e32 v4, v4, v249, vcc
	v_cndmask_b32_e32 v3, v3, v250, vcc
	v_cndmask_b32_e32 v2, v2, v248, vcc
	s_add_i32 s99, s14, 0xffffeff0
	v_cmp_eq_u32_e32 vcc, s99, v114
	s_nop 1
	v_cndmask_b32_e32 v0, v0, v252, vcc
	v_cndmask_b32_e32 v4, v4, v254, vcc
	v_cndmask_b32_e32 v3, v3, v255, vcc
	v_cndmask_b32_e32 v2, v2, v253, vcc
	s_cmp_eq_u32 s14, 0x10100
	s_cbranch_scc0 .Lrt_loop
	v_cndmask_b32_e64 v0, v115, v0, s[6:7]
	ds_bpermute_b32 v1, v105, v0
	v_max_f32_e32 v5, v0, v0
	v_and_b32_e32 v7, 0x7fc, v90
	s_waitcnt lgkmcnt(0)
	v_max_f32_e32 v1, v1, v1
	v_max_f32_e32 v1, v5, v1
	ds_bpermute_b32 v5, v106, v1
	s_waitcnt lgkmcnt(0)
	v_max_f32_e32 v5, v5, v5
	v_max_f32_e32 v1, v1, v5
	ds_bpermute_b32 v5, v107, v1
	s_waitcnt lgkmcnt(0)
	v_max_f32_e32 v5, v5, v5
	v_max_f32_e32 v1, v1, v5
	ds_bpermute_b32 v5, v108, v1
	s_waitcnt lgkmcnt(0)
	v_max_f32_e32 v5, v5, v5
	v_max_f32_e32 v1, v1, v5
	ds_bpermute_b32 v1, v113, v1
	s_waitcnt lgkmcnt(0)
	v_sub_f32_e32 v0, v0, v1
	v_mul_f32_e32 v1, 0x3fb8aa3b, v0
	v_fma_f32 v5, v0, s27, -v1
	v_rndne_f32_e32 v6, v1
	v_fmac_f32_e32 v5, 0x32a5705f, v0
	v_sub_f32_e32 v1, v1, v6
	v_add_f32_e32 v1, v1, v5
	v_cvt_i32_f32_e32 v6, v6
	v_exp_f32_e32 v1, v1
	v_cmp_ngt_f32_e32 vcc, s30, v0
	v_ldexp_f32 v1, v1, v6
	s_nop 0
	v_cndmask_b32_e32 v1, 0, v1, vcc
	v_cmp_nlt_f32_e32 vcc, s31, v0
	s_nop 1
	v_cndmask_b32_e32 v5, v116, v1, vcc
	v_cndmask_b32_e64 v0, 0, v5, s[6:7]
	ds_bpermute_b32 v1, v105, v0
	s_waitcnt lgkmcnt(0)
	v_add_f32_e32 v0, v0, v1
	ds_bpermute_b32 v1, v106, v0
	s_waitcnt lgkmcnt(0)
	v_add_f32_e32 v0, v0, v1
	ds_bpermute_b32 v1, v107, v0
	s_waitcnt lgkmcnt(0)
	v_add_f32_e32 v1, v0, v1
	ds_bpermute_b32 v6, v108, v1
	v_lshl_add_u32 v0, v68, 4, v196
	v_lshlrev_b32_e32 v68, 2, v7
	s_waitcnt lgkmcnt(0)
	v_add_f32_e32 v1, v1, v6
	ds_bpermute_b32 v6, v113, v1
	v_ashrrev_i32_e32 v1, 31, v0
	v_lshlrev_b64 v[0:1], 13, v[0:1]
	v_lshl_add_u64 v[0:1], s[18:19], 0, v[0:1]
	s_and_saveexec_b64 s[14:15], s[6:7]
	s_cbranch_execz .LBB0_1026
	s_waitcnt lgkmcnt(0)
	v_div_scale_f32 v7, s[16:17], v6, v6, v5
	v_rcp_f32_e32 v8, v7
	v_div_scale_f32 v9, vcc, v5, v6, v5
	v_fma_f32 v10, -v7, v8, 1.0
	v_fmac_f32_e32 v8, v10, v8
	v_mul_f32_e32 v10, v9, v8
	v_fma_f32 v11, -v7, v10, v9
	v_fmac_f32_e32 v10, v11, v8
	v_fma_f32 v7, -v7, v10, v9
	v_div_fmas_f32 v7, v7, v8, v10
	v_div_fixup_f32 v5, v7, v6, v5
	v_lshl_add_u64 v[6:7], v[0:1], 0, v[68:69]
	global_store_dword v[6:7], v5, off
